# diff loop hot path straightened: rare far-path fix-up and rare O/l rescale blocks moved out of line behind the loop's closing branch
# speedup vs baseline: 1.0149x; 1.0072x over previous
.LBB0_258_a:
	s_andn2_saveexec_b64 s[22:23], s[22:23]
	s_cbranch_execz .LBB0_260_a
	v_sub_f32_e32 v243, v198, v226
	v_fmamk_f32 v112, v96, 0x3e38aa3b, v243
	v_fmamk_f32 v113, v97, 0x3e38aa3b, v243
	v_fmamk_f32 v114, v98, 0x3e38aa3b, v243
	v_fmamk_f32 v115, v99, 0x3e38aa3b, v243
	v_fmamk_f32 v116, v100, 0x3e38aa3b, v243
	v_fmamk_f32 v117, v101, 0x3e38aa3b, v243
	v_fmamk_f32 v118, v102, 0x3e38aa3b, v243
	v_fmamk_f32 v119, v103, 0x3e38aa3b, v243
	v_fmamk_f32 v120, v104, 0x3e38aa3b, v243
	v_fmamk_f32 v121, v105, 0x3e38aa3b, v243
	v_fmamk_f32 v122, v106, 0x3e38aa3b, v243
	v_fmamk_f32 v123, v107, 0x3e38aa3b, v243
	v_fmamk_f32 v124, v108, 0x3e38aa3b, v243
	v_fmamk_f32 v125, v109, 0x3e38aa3b, v243
	v_fmamk_f32 v126, v110, 0x3e38aa3b, v243
	v_fmamk_f32 v127, v111, 0x3e38aa3b, v243
	v_max3_f32 v244, v96, v97, v98
	v_max3_f32 v245, v99, v100, v101
	v_max3_f32 v244, v244, v102, v103
	v_max3_f32 v245, v245, v104, v105
	v_max3_f32 v244, v244, v106, v107
	v_max3_f32 v245, v245, v108, v109
	v_max3_f32 v244, v244, v110, v111
	v_fmamk_f32 v128, v80, 0x3e38aa3b, v243
	v_fmamk_f32 v129, v81, 0x3e38aa3b, v243
	v_fmamk_f32 v130, v82, 0x3e38aa3b, v243
	v_fmamk_f32 v131, v83, 0x3e38aa3b, v243
	v_fmamk_f32 v132, v84, 0x3e38aa3b, v243
	v_fmamk_f32 v133, v85, 0x3e38aa3b, v243
	v_fmamk_f32 v134, v86, 0x3e38aa3b, v243
	v_fmamk_f32 v135, v87, 0x3e38aa3b, v243
	v_fmamk_f32 v136, v88, 0x3e38aa3b, v243
	v_fmamk_f32 v137, v89, 0x3e38aa3b, v243
	v_fmamk_f32 v138, v90, 0x3e38aa3b, v243
	v_fmamk_f32 v139, v91, 0x3e38aa3b, v243
	v_fmamk_f32 v140, v92, 0x3e38aa3b, v243
	v_fmamk_f32 v141, v93, 0x3e38aa3b, v243
	v_fmamk_f32 v142, v94, 0x3e38aa3b, v243
	v_fmamk_f32 v143, v95, 0x3e38aa3b, v243
	v_max3_f32 v244, v244, v80, v81
	v_max3_f32 v245, v245, v82, v83
	v_max3_f32 v244, v244, v84, v85
	v_max3_f32 v245, v245, v86, v87
	v_max3_f32 v244, v244, v88, v89
	v_max3_f32 v245, v245, v90, v91
	v_max3_f32 v244, v244, v92, v93
	v_max3_f32 v245, v245, v94, v95
	v_max_f32_e32 v244, v244, v245
	v_mov_b32_e32 v245, v244
	s_nop 1
	v_permlane32_swap_b32_e32 v244, v245
	v_max_f32_e32 v244, v244, v245
	v_fmamk_f32 v244, v244, 0x3e38aa3b, v198
	v_sub_f32_e32 v245, v244, v226
	v_cmp_lt_f32_e32 vcc, s45, v245
	v_max_f32_e32 v244, v226, v244
	s_nop 0
	v_cndmask_b32_e32 v227, v226, v244, vcc
	s_nop 2
	s_cbranch_vccnz .Ldf_rare_ff_a
.Ldf_far_nofix_a:
.LBB0_260_a:
	s_or_b64 exec, exec, s[22:23]
	v_cmp_neq_f32_e32 vcc, v227, v226
	ds_read_b64_tr_b16 v[80:81], v199 offset:20480
	ds_read_b64_tr_b16 v[82:83], v210 offset:22528
	ds_read_b64_tr_b16 v[84:85], v211 offset:20480
	ds_read_b64_tr_b16 v[86:87], v212 offset:22528
	ds_read_b64_tr_b16 v[88:89], v213 offset:20480
	ds_read_b64_tr_b16 v[90:91], v214 offset:22528
	ds_read_b64_tr_b16 v[92:93], v215 offset:20480
	ds_read_b64_tr_b16 v[94:95], v216 offset:22528
	v_exp_f32_e32 v104, v112
	v_exp_f32_e32 v105, v113
	v_exp_f32_e32 v106, v114
	v_exp_f32_e32 v107, v115
	v_exp_f32_e32 v108, v116
	v_exp_f32_e32 v109, v117
	v_exp_f32_e32 v110, v118
	v_exp_f32_e32 v111, v119
	s_cbranch_vccnz .Ldf_rare_rs_a

.Ldf_far_nofix_b:
.LBB0_260_b:
	s_or_b64 exec, exec, s[22:23]
	v_cmp_neq_f32_e32 vcc, v227, v226
	ds_read_b64_tr_b16 v[80:81], v199 offset:53248
	ds_read_b64_tr_b16 v[82:83], v210 offset:55296
	ds_read_b64_tr_b16 v[84:85], v211 offset:53248
	ds_read_b64_tr_b16 v[86:87], v212 offset:55296
	ds_read_b64_tr_b16 v[88:89], v213 offset:53248
	ds_read_b64_tr_b16 v[90:91], v214 offset:55296
	ds_read_b64_tr_b16 v[92:93], v215 offset:53248
	ds_read_b64_tr_b16 v[94:95], v216 offset:55296
	v_exp_f32_e32 v104, v112
	v_exp_f32_e32 v105, v113
	v_exp_f32_e32 v106, v114
	v_exp_f32_e32 v107, v115
	v_exp_f32_e32 v108, v116
	v_exp_f32_e32 v109, v117
	v_exp_f32_e32 v110, v118
	v_exp_f32_e32 v111, v119
	s_cbranch_vccnz .Ldf_rare_rs_b

.Ldf_rare_ff_a:
	v_sub_f32_e32 v243, v198, v227
	v_fmamk_f32 v112, v96, 0x3e38aa3b, v243
	v_fmamk_f32 v128, v80, 0x3e38aa3b, v243
	v_fmamk_f32 v113, v97, 0x3e38aa3b, v243
	v_fmamk_f32 v129, v81, 0x3e38aa3b, v243
	v_fmamk_f32 v114, v98, 0x3e38aa3b, v243
	v_fmamk_f32 v130, v82, 0x3e38aa3b, v243
	v_fmamk_f32 v115, v99, 0x3e38aa3b, v243
	v_fmamk_f32 v131, v83, 0x3e38aa3b, v243
	v_fmamk_f32 v116, v100, 0x3e38aa3b, v243
	v_fmamk_f32 v132, v84, 0x3e38aa3b, v243
	v_fmamk_f32 v117, v101, 0x3e38aa3b, v243
	v_fmamk_f32 v133, v85, 0x3e38aa3b, v243
	v_fmamk_f32 v118, v102, 0x3e38aa3b, v243
	v_fmamk_f32 v134, v86, 0x3e38aa3b, v243
	v_fmamk_f32 v119, v103, 0x3e38aa3b, v243
	v_fmamk_f32 v135, v87, 0x3e38aa3b, v243
	v_fmamk_f32 v120, v104, 0x3e38aa3b, v243
	v_fmamk_f32 v136, v88, 0x3e38aa3b, v243
	v_fmamk_f32 v121, v105, 0x3e38aa3b, v243
	v_fmamk_f32 v137, v89, 0x3e38aa3b, v243
	v_fmamk_f32 v122, v106, 0x3e38aa3b, v243
	v_fmamk_f32 v138, v90, 0x3e38aa3b, v243
	v_fmamk_f32 v123, v107, 0x3e38aa3b, v243
	v_fmamk_f32 v139, v91, 0x3e38aa3b, v243
	v_fmamk_f32 v124, v108, 0x3e38aa3b, v243
	v_fmamk_f32 v140, v92, 0x3e38aa3b, v243
	v_fmamk_f32 v125, v109, 0x3e38aa3b, v243
	v_fmamk_f32 v141, v93, 0x3e38aa3b, v243
	v_fmamk_f32 v126, v110, 0x3e38aa3b, v243
	v_fmamk_f32 v142, v94, 0x3e38aa3b, v243
	v_fmamk_f32 v127, v111, 0x3e38aa3b, v243
	v_fmamk_f32 v143, v95, 0x3e38aa3b, v243
	s_branch .Ldf_far_nofix_a
.Ldf_rare_rs_a:
	v_sub_f32_e32 v246, v226, v227
	v_exp_f32_e32 v246, v246
	s_nop 0
	v_mul_f32_e32 v219, v219, v246
	v_pk_mul_f32 v[78:79], v[78:79], v[246:247] op_sel_hi:[1,0]
	v_pk_mul_f32 v[76:77], v[76:77], v[246:247] op_sel_hi:[1,0]
	v_pk_mul_f32 v[74:75], v[74:75], v[246:247] op_sel_hi:[1,0]
	v_pk_mul_f32 v[72:73], v[72:73], v[246:247] op_sel_hi:[1,0]
	v_pk_mul_f32 v[70:71], v[70:71], v[246:247] op_sel_hi:[1,0]
	v_pk_mul_f32 v[68:69], v[68:69], v[246:247] op_sel_hi:[1,0]
	v_pk_mul_f32 v[66:67], v[66:67], v[246:247] op_sel_hi:[1,0]
	v_pk_mul_f32 v[64:65], v[64:65], v[246:247] op_sel_hi:[1,0]
	v_pk_mul_f32 v[62:63], v[62:63], v[246:247] op_sel_hi:[1,0]
	v_pk_mul_f32 v[60:61], v[60:61], v[246:247] op_sel_hi:[1,0]
	v_pk_mul_f32 v[58:59], v[58:59], v[246:247] op_sel_hi:[1,0]
	v_pk_mul_f32 v[56:57], v[56:57], v[246:247] op_sel_hi:[1,0]
	v_pk_mul_f32 v[54:55], v[54:55], v[246:247] op_sel_hi:[1,0]
	v_pk_mul_f32 v[52:53], v[52:53], v[246:247] op_sel_hi:[1,0]
	v_pk_mul_f32 v[50:51], v[50:51], v[246:247] op_sel_hi:[1,0]
	v_pk_mul_f32 v[48:49], v[48:49], v[246:247] op_sel_hi:[1,0]
	v_pk_mul_f32 v[46:47], v[46:47], v[246:247] op_sel_hi:[1,0]
	v_pk_mul_f32 v[44:45], v[44:45], v[246:247] op_sel_hi:[1,0]
	v_pk_mul_f32 v[42:43], v[42:43], v[246:247] op_sel_hi:[1,0]
	v_pk_mul_f32 v[40:41], v[40:41], v[246:247] op_sel_hi:[1,0]
	v_pk_mul_f32 v[38:39], v[38:39], v[246:247] op_sel_hi:[1,0]
	v_pk_mul_f32 v[36:37], v[36:37], v[246:247] op_sel_hi:[1,0]
	v_pk_mul_f32 v[34:35], v[34:35], v[246:247] op_sel_hi:[1,0]
	v_pk_mul_f32 v[32:33], v[32:33], v[246:247] op_sel_hi:[1,0]
	v_pk_mul_f32 v[30:31], v[30:31], v[246:247] op_sel_hi:[1,0]
	v_pk_mul_f32 v[28:29], v[28:29], v[246:247] op_sel_hi:[1,0]
	v_pk_mul_f32 v[26:27], v[26:27], v[246:247] op_sel_hi:[1,0]
	v_pk_mul_f32 v[24:25], v[24:25], v[246:247] op_sel_hi:[1,0]
	v_pk_mul_f32 v[22:23], v[22:23], v[246:247] op_sel_hi:[1,0]
	v_pk_mul_f32 v[20:21], v[20:21], v[246:247] op_sel_hi:[1,0]
	v_pk_mul_f32 v[18:19], v[18:19], v[246:247] op_sel_hi:[1,0]
	v_pk_mul_f32 v[16:17], v[16:17], v[246:247] op_sel_hi:[1,0]
	s_branch .Ldf_norescale_a
